# v47 + rstd cached across tiles of a row block; on cache hits the in-proj/gates epilogue no longer waits for the next tile's DMA prefetch
# baseline (speedup 1.0000x reference)
;     ...
;         for (int m = 0; m < 4; ++m) { float sq = (p[ai][m].x + p[ai][m].y) + (p[ai][m].z + p[ai][m].w);
;             sq += __shfl_xor(sq, 16); sq += __shfl_xor(sq, 32);
;             const float rs = __builtin_amdgcn_rsqf(sq * (1.0f / DM) + EPS) * mul;
;     __device__ __forceinline__ void operator()(f32x4 (&acc)[2][2][4][2], const Unit& u, int wr, int wc, int fr, int fq) const {
;     ...
;         const int row0 = u.pm * BM + wr * 64 + fr;
;         const int colt = (MODE == 1) ? gate_zcol(u.pn) : u.pn * BM;
;         const int col0 = colt + wc * 32 + 8 * fq;
.Lrc0_skip:
	v_and_b32_e32 v154, 64, v249
	v_xor_b32_e32 v0, 16, v249
	v_add_u32_e32 v154, 64, v154
	v_cmp_lt_i32_e32 vcc, v0, v154
	v_xor_b32_e32 v155, 32, v249
	s_lshl_b32 s41, s56, 8
	v_cndmask_b32_e32 v0, v249, v0, vcc
	v_cmp_lt_i32_e32 vcc, v155, v154
	v_lshlrev_b32_e32 v0, 2, v0
	s_lshl_b32 s40, s40, 5
	v_cndmask_b32_e32 v154, v249, v155, vcc
	v_lshlrev_b32_e32 v188, 2, v154
	s_add_i32 s43, s40, s41
	s_cselect_b32 s99, 1, 0
	s_cmp_lg_u32 s98, 0
	s_cbranch_scc1 .Lrw0_nowait
	s_waitcnt vmcnt(0)
	s_branch .Lrw0_join

; __device__ __forceinline__ unsigned cvt_pk_bf16(float lo, float hi) { unsigned r; asm volatile("s_nop 1\n\tv_cvt_pk_bf16_f32 %0, %1, %2" : "=v"(r) : "v"(lo), "v"(hi)); return r; }
;     ...
;         for (int m = 0; m < 4; ++m) { float sq = (p[ai][m].x + p[ai][m].y) + (p[ai][m].z + p[ai][m].w);
;             sq += __shfl_xor(sq, 16); sq += __shfl_xor(sq, 32);
;             const float rs = __builtin_amdgcn_rsqf(sq * (1.0f / DM) + EPS) * mul;
; #pragma unroll
;             for (int bj = 0; bj < 2; ++bj)
; #pragma unroll
;                 for (int n = 0; n < 2; ++n) acc[ai][bj][m][n] = acc[ai][bj][m][n] * rs; }
;     __device__ __forceinline__ void operator()(f32x4 (&acc)[2][2][4][2], const Unit& u, int wr, int wc, int fr, int fq) const {
;     ...
;                     if (u.pn * BM + bj * HALF + wc * 32 + 8 * fq < ZGA + 16) {
;                     u32x4 w; w.x = cvt_pk_bf16(v0[0], v0[1]); w.y = cvt_pk_bf16(v0[2], v0[3]); w.z = cvt_pk_bf16(v1[0], v1[1]); w.w = cvt_pk_bf16(v1[2], v1[3]);
;                     *(u32x4*)(rowp + bj * HALF) = w; } } } }
.Lrw0_join:
	s_cmp_lg_u32 s99, 0
	s_mov_b32 s99, s98
	v_mov_b32_e32 v154, v159
	v_mov_b32_e32 v155, v160
	v_mov_b32_e32 v159, v161
	v_pk_add_f32 v[154:155], v[154:155], v[158:159]
	v_mov_b32_e32 v158, v163
	v_mov_b32_e32 v159, v164
	v_mov_b32_e32 v163, v165
	v_pk_add_f32 v[158:159], v[158:159], v[162:163]
	v_add_f32_e32 v154, v154, v155
	v_add_f32_e32 v158, v158, v159
	ds_bpermute_b32 v159, v0, v158
	ds_bpermute_b32 v155, v0, v154
	s_waitcnt lgkmcnt(1)
	v_add_f32_e32 v164, v158, v159
	v_mov_b32_e32 v158, v177
	v_mov_b32_e32 v159, v178
	v_mov_b32_e32 v177, v179
	v_pk_add_f32 v[158:159], v[158:159], v[176:177]
	s_waitcnt lgkmcnt(0)
	v_add_f32_e32 v154, v154, v155
	v_add_f32_e32 v158, v158, v159
	ds_bpermute_b32 v159, v0, v158
	ds_bpermute_b32 v155, v188, v154
	v_mov_b32_e32 v166, v139
	v_mov_b32_e32 v167, v140
	v_mov_b32_e32 v139, v141
	s_waitcnt lgkmcnt(1)
	v_add_f32_e32 v162, v158, v159
	v_mov_b32_e32 v158, v181
	v_mov_b32_e32 v159, v182
	v_mov_b32_e32 v181, v183
	v_mov_b32_e32 v140, v135
	v_mov_b32_e32 v141, v136
	v_mov_b32_e32 v135, v137
	v_pk_add_f32 v[158:159], v[158:159], v[180:181]
	v_pk_add_f32 v[134:135], v[140:141], v[134:135]
	v_add_f32_e32 v158, v158, v159
	v_add_f32_e32 v134, v134, v135
	ds_bpermute_b32 v159, v0, v158
	ds_bpermute_b32 v135, v0, v134
	v_pk_add_f32 v[138:139], v[166:167], v[138:139]
	s_waitcnt lgkmcnt(2)
	v_add_f32_e32 v154, v154, v155
	v_add_f32_e32 v138, v138, v139
	s_waitcnt lgkmcnt(1)
	v_add_f32_e32 v160, v158, v159
	v_mov_b32_e32 v158, v185
	v_mov_b32_e32 v159, v186
	v_mov_b32_e32 v185, v187
	s_waitcnt lgkmcnt(0)
	v_add_f32_e32 v136, v134, v135
	v_mov_b32_e32 v134, v131
	v_mov_b32_e32 v135, v132
	v_mov_b32_e32 v131, v133
	v_pk_add_f32 v[158:159], v[158:159], v[184:185]
	v_pk_add_f32 v[130:131], v[134:135], v[130:131]
	v_add_f32_e32 v158, v158, v159
	v_add_f32_e32 v130, v130, v131
	ds_bpermute_b32 v159, v0, v158
	ds_bpermute_b32 v139, v0, v138
	ds_bpermute_b32 v0, v0, v130
	v_fmamk_f32 v154, v154, 0x3a800000, v247
	v_rsq_f32_e32 v154, v154
	s_nop 0
	v_cndmask_b32_e64 v154, v154, v226, s[98:99]
	v_mov_b32_e32 v226, v154
	s_waitcnt lgkmcnt(2)
	v_add_f32_e32 v158, v158, v159
	s_waitcnt lgkmcnt(1)
	v_add_f32_e32 v138, v138, v139
	s_waitcnt lgkmcnt(0)
	v_add_f32_e32 v0, v130, v0
	ds_bpermute_b32 v165, v188, v164
	ds_bpermute_b32 v163, v188, v162
	ds_bpermute_b32 v161, v188, v160
	ds_bpermute_b32 v159, v188, v158
	ds_bpermute_b32 v139, v188, v138
	ds_bpermute_b32 v137, v188, v136
	ds_bpermute_b32 v134, v188, v0
	v_lshlrev_b32_e32 v132, 3, v173
	v_or_b32_e32 v131, s11, v172
	v_or_b32_e32 v130, s43, v132
	v_add_u32_e32 v135, s10, v131
	v_or_b32_e32 v140, s40, v132
	v_mov_b64_e32 v[132:133], s[68:69]
	v_mad_i64_i32 v[132:133], s[10:11], v135, s74, v[132:133]
	v_ashrrev_i32_e32 v131, 31, v130
	v_add_u32_e32 v140, s41, v140
	s_movk_i32 s10, 0x1110
	v_mov_b32_e32 v155, v154
	v_lshl_add_u64 v[132:133], v[130:131], 1, v[132:133]
	v_cmp_gt_i32_e32 vcc, s10, v140
	s_and_saveexec_b64 s[10:11], vcc
	s_cbranch_execz .LBB0_393
	v_mov_b32_e32 v166, v154
	v_mov_b32_e32 v167, v154
	v_pk_mul_f32 v[176:177], v[124:125], v[166:167]
	v_pk_mul_f32 v[124:125], v[122:123], v[154:155]
	v_pk_mul_f32 v[122:123], v[126:127], v[154:155]
	v_pk_mul_f32 v[128:129], v[128:129], v[166:167]
	s_nop 1
	v_cvt_pk_bf16_f32 v122, v122, v123
	s_nop 0
	s_nop 1
	v_cvt_pk_bf16_f32 v123, v128, v129
	s_nop 1
	v_cvt_pk_bf16_f32 v124, v124, v125
	s_nop 1
	v_cvt_pk_bf16_f32 v125, v176, v177
	global_store_dwordx4 v[132:133], v[122:125], off

;     ...
;         for (int m = 0; m < 4; ++m) { float sq = (p[ai][m].x + p[ai][m].y) + (p[ai][m].z + p[ai][m].w);
;             sq += __shfl_xor(sq, 16); sq += __shfl_xor(sq, 32);
.Lrc1_skip:
	v_and_b32_e32 v166, 64, v249
	v_xor_b32_e32 v0, 16, v249
	v_add_u32_e32 v166, 64, v166
	v_cmp_lt_i32_e32 vcc, v0, v166
	s_mov_b64 s[10:11], -1
	s_cmp_gt_i32 s56, 3
	v_cndmask_b32_e32 v0, v249, v0, vcc
	v_lshlrev_b32_e32 v172, 2, v0
	v_xor_b32_e32 v0, 32, v249
	v_cmp_lt_i32_e32 vcc, v0, v166
	s_mov_b32 s94, s96
	s_cselect_b32 s99, 1, 0
	s_cmp_lg_u32 s98, 0
	s_cbranch_scc1 .Lrw1_nowait
	s_waitcnt vmcnt(0)
	s_branch .Lrw1_join

;     ...
;         for (int m = 0; m < 4; ++m) { float sq = (p[ai][m].x + p[ai][m].y) + (p[ai][m].z + p[ai][m].w);
;             sq += __shfl_xor(sq, 16); sq += __shfl_xor(sq, 32);
.Lrw1_join:
	s_cmp_lg_u32 s99, 0
	s_mov_b32 s99, s98
	v_mov_b32_e32 v166, v159
	v_mov_b32_e32 v167, v160
	v_mov_b32_e32 v159, v161
	v_pk_add_f32 v[158:159], v[166:167], v[158:159]
	v_cndmask_b32_e32 v0, v249, v0, vcc
	v_mov_b32_e32 v160, v163
	v_mov_b32_e32 v161, v164
	v_mov_b32_e32 v163, v165
	v_pk_add_f32 v[160:161], v[160:161], v[162:163]
	v_lshlrev_b32_e32 v173, 2, v0
	v_mov_b32_e32 v162, v177
	v_mov_b32_e32 v163, v178
	v_mov_b32_e32 v177, v179
	v_pk_add_f32 v[162:163], v[162:163], v[176:177]
	v_add_f32_e32 v0, v158, v159
	v_mov_b32_e32 v164, v181
	v_mov_b32_e32 v165, v182
	v_mov_b32_e32 v181, v183
	v_pk_add_f32 v[164:165], v[164:165], v[180:181]
	v_add_f32_e32 v159, v160, v161
	v_mov_b32_e32 v166, v185
	v_mov_b32_e32 v167, v186
	v_mov_b32_e32 v185, v187
	v_pk_add_f32 v[166:167], v[166:167], v[184:185]
	v_add_f32_e32 v161, v162, v163
	v_mov_b32_e32 v176, v139
	v_mov_b32_e32 v177, v140
	v_mov_b32_e32 v139, v141
	v_pk_add_f32 v[138:139], v[176:177], v[138:139]
	v_add_f32_e32 v163, v164, v165
	v_add_f32_e32 v165, v166, v167
	v_add_f32_e32 v138, v138, v139
	ds_bpermute_b32 v158, v172, v0
	ds_bpermute_b32 v160, v172, v159
	v_mov_b32_e32 v140, v135
	v_mov_b32_e32 v141, v136
	v_mov_b32_e32 v135, v137
	v_mov_b32_e32 v136, v131
	v_mov_b32_e32 v137, v132
	v_mov_b32_e32 v131, v133
	v_pk_add_f32 v[134:135], v[140:141], v[134:135]
	v_pk_add_f32 v[130:131], v[136:137], v[130:131]
	v_add_f32_e32 v134, v134, v135
	v_add_f32_e32 v130, v130, v131
	ds_bpermute_b32 v162, v172, v161
	ds_bpermute_b32 v164, v172, v163
	ds_bpermute_b32 v166, v172, v165
	ds_bpermute_b32 v139, v172, v138
	ds_bpermute_b32 v135, v172, v134
	ds_bpermute_b32 v131, v172, v130
	s_waitcnt lgkmcnt(7)
	v_add_f32_e32 v0, v0, v158
	s_waitcnt lgkmcnt(6)
	v_add_f32_e32 v159, v159, v160
	s_waitcnt lgkmcnt(5)
	v_add_f32_e32 v161, v161, v162
	s_waitcnt lgkmcnt(4)
	v_add_f32_e32 v163, v163, v164
	s_waitcnt lgkmcnt(3)
	v_add_f32_e32 v165, v165, v166
	s_waitcnt lgkmcnt(2)
	v_add_f32_e32 v138, v138, v139
	s_waitcnt lgkmcnt(1)
	v_add_f32_e32 v134, v134, v135
	s_waitcnt lgkmcnt(0)
	v_add_f32_e32 v136, v130, v131
	ds_bpermute_b32 v158, v173, v0
	ds_bpermute_b32 v160, v173, v159
	ds_bpermute_b32 v162, v173, v161
	ds_bpermute_b32 v164, v173, v163
	ds_bpermute_b32 v166, v173, v165
	ds_bpermute_b32 v139, v173, v138
	ds_bpermute_b32 v135, v173, v134
	ds_bpermute_b32 v137, v173, v136
	s_cbranch_scc0 .LBB0_694
	s_cmp_gt_u32 s56, 5
	s_cbranch_scc0 .LBB0_691
	s_cmp_gt_u32 s56, 7
	s_cbranch_scc0 .LBB0_688
	s_cmp_gt_u32 s56, 9
	s_cbranch_scc0 .LBB0_685
	s_cmp_eq_u32 s56, 10
	s_movk_i32 s10, 0x1100
	s_cselect_b32 s50, 0x1000, s10
	s_mov_b64 s[10:11], 0
